# ml_post: per-head parameter vectors loaded once before the token loop (register copies in the loop)
# baseline (speedup 1.0000x reference)
.LBB0_869:
	s_or_b64 exec, exec, s[2:3]
	s_mov_b64 s[4:5], s[66:67]
	s_waitcnt vmcnt(7) lgkmcnt(0)
	v_mov_b32_e32 v2, v178
	s_mov_b32 s2, s68
	v_mov_b32_e32 v1, v178
	s_barrier
	s_mov_b32 s6, s70
	v_ashrrev_i32_e32 v1, 6, v1
	v_lshl_add_u32 v42, s2, 3, v1
	s_mov_b32 s2, 0x8000
	v_cmp_gt_i32_e32 vcc, s2, v42
	s_and_saveexec_b64 s[2:3], vcc
	s_movk_i32 s14, 0x7fff
	s_mov_b32 s16, 0x3b000000
	s_cbranch_execz .LBB0_872
	v_lshlrev_b32_e32 v1, 5, v2
	v_cmp_lt_i32_e32 vcc, v241, v235
	v_and_b32_e32 v4, 0x7e0, v1
	s_load_dwordx4 s[8:11], s[4:5], 0xf8
	s_nop 0
	s_load_dwordx2 s[4:5], s[4:5], 0x120
	v_cndmask_b32_e32 v1, v234, v241, vcc
	v_cmp_lt_i32_e32 vcc, v240, v235
	v_and_b32_e32 v2, 63, v2
	v_ashrrev_i32_e32 v43, 31, v42
	v_cndmask_b32_e32 v3, v234, v240, vcc
	v_lshlrev_b32_e32 v116, 2, v3
	v_xor_b32_e32 v3, 8, v234
	v_cmp_lt_i32_e32 vcc, v3, v235
	s_lshl_b32 s6, s6, 3
	v_mov_b32_e32 v5, v0
	v_cndmask_b32_e32 v3, v234, v3, vcc
	v_lshlrev_b32_e32 v117, 2, v3
	v_xor_b32_e32 v3, 4, v234
	v_cmp_lt_i32_e32 vcc, v3, v235
	v_lshlrev_b32_e32 v56, 4, v2
	s_waitcnt lgkmcnt(0)
	v_lshl_add_u64 v[44:45], s[8:9], 0, v[4:5]
	v_cndmask_b32_e32 v3, v234, v3, vcc
	v_lshlrev_b32_e32 v118, 2, v3
	v_xor_b32_e32 v3, 2, v234
	v_cmp_lt_i32_e32 vcc, v3, v235
	v_lshl_add_u64 v[46:47], s[10:11], 0, v[4:5]
	s_waitcnt vmcnt(6)
	v_or_b32_e32 v6, 0x1000, v4
	v_cndmask_b32_e32 v3, v234, v3, vcc
	v_lshlrev_b32_e32 v119, 2, v3
	v_xor_b32_e32 v3, 1, v234
	v_cmp_lt_i32_e32 vcc, v3, v235
	v_mov_b32_e32 v7, v0
	v_or_b32_e32 v4, 0x1800, v4
	v_cndmask_b32_e32 v3, v234, v3, vcc
	v_lshlrev_b32_e32 v120, 2, v3
	v_lshlrev_b64 v[2:3], 12, v[42:43]
	v_lshl_add_u64 v[58:59], s[4:5], 0, v[2:3]
	s_ashr_i32 s7, s6, 31
	v_lshlrev_b64 v[2:3], 13, v[42:43]
	v_lshlrev_b32_e32 v1, 2, v1
	v_lshl_add_u64 v[48:49], s[8:9], 0, v[6:7]
	v_lshl_add_u64 v[50:51], s[10:11], 0, v[6:7]
	v_lshl_add_u64 v[52:53], s[8:9], 0, v[4:5]
	v_lshl_add_u64 v[54:55], s[10:11], 0, v[4:5]
	v_mov_b32_e32 v57, v0
	s_lshl_b64 s[8:9], s[6:7], 12
	v_lshl_add_u64 v[60:61], s[4:5], 0, v[2:3]
	s_lshl_b64 s[10:11], s[6:7], 13
	s_mov_b64 s[12:13], 0
	global_load_dwordx4 v[132:135], v[44:45], off offset:16
	global_load_dwordx4 v[136:139], v[44:45], off
	global_load_dwordx4 v[140:143], v[46:47], off offset:16
	global_load_dwordx4 v[144:147], v[46:47], off
	global_load_dwordx4 v[148:151], v[44:45], off offset:2064
	global_load_dwordx4 v[152:155], v[44:45], off offset:2048
	global_load_dwordx4 v[156:159], v[46:47], off offset:2064
	global_load_dwordx4 v[160:163], v[46:47], off offset:2048
	global_load_dwordx4 v[164:167], v[48:49], off offset:16
	global_load_dwordx4 v[168:171], v[48:49], off
	global_load_dwordx4 v[172:175], v[50:51], off offset:16
	global_load_dwordx4 v[186:189], v[50:51], off
	global_load_dwordx4 v[190:193], v[52:53], off offset:16
	global_load_dwordx4 v[194:197], v[52:53], off
	global_load_dwordx4 v[198:201], v[54:55], off offset:16
	global_load_dwordx4 v[202:205], v[54:55], off
	s_waitcnt vmcnt(0)
.LBB0_871:
	v_lshl_add_u64 v[2:3], v[60:61], 0, v[56:57]
	v_add_co_u32_e32 v4, vcc, 0x3200000, v2
	s_mov_b32 s4, 0x358637bd
	s_nop 0
	v_addc_co_u32_e32 v5, vcc, 0, v3, vcc
	v_add_co_u32_e32 v62, vcc, 0x3201000, v2
	global_load_dwordx4 v[74:77], v[4:5], off
	s_nop 0
	v_addc_co_u32_e32 v63, vcc, 0, v3, vcc
	global_load_dwordx4 v[78:81], v[62:63], off
	v_lshl_add_u64 v[2:3], v[58:59], 0, v[56:57]
	v_add_co_u32_e32 v2, vcc, 0x13200000, v2
	v_add_u32_e32 v42, s6, v42
	s_nop 0
	v_addc_co_u32_e32 v3, vcc, 0, v3, vcc
	global_load_dwordx4 v[82:85], v[2:3], off
	global_load_dwordx4 v[102:105], v[4:5], off offset:1024
	global_load_dwordx4 v[106:109], v[62:63], off offset:1024
	global_load_dwordx4 v[110:113], v[2:3], off offset:1024
	global_load_dwordx4 v[22:25], v[4:5], off offset:2048
	global_load_dwordx4 v[18:21], v[62:63], off offset:2048
	global_load_dwordx4 v[14:17], v[2:3], off offset:2048
	global_load_dwordx4 v[10:13], v[4:5], off offset:3072
	global_load_dwordx4 v[6:9], v[62:63], off offset:3072
	s_nop 0
	global_load_dwordx4 v[2:5], v[2:3], off offset:3072
	s_nop 0
	v_mov_b32_e32 v26, v132
	v_mov_b32_e32 v27, v133
	v_mov_b32_e32 v28, v134
	v_mov_b32_e32 v29, v135
	v_mov_b32_e32 v34, v136
	v_mov_b32_e32 v35, v137
	v_mov_b32_e32 v36, v138
	v_mov_b32_e32 v37, v139
	v_mov_b32_e32 v30, v140
	v_mov_b32_e32 v31, v141
	v_mov_b32_e32 v32, v142
	v_mov_b32_e32 v33, v143
	v_mov_b32_e32 v38, v144
	v_mov_b32_e32 v39, v145
	v_mov_b32_e32 v40, v146
	v_mov_b32_e32 v41, v147
	v_lshl_add_u64 v[58:59], v[58:59], 0, s[8:9]
	v_lshl_add_u64 v[60:61], v[60:61], 0, s[10:11]
	s_waitcnt vmcnt(9)
	v_lshlrev_b32_e32 v66, 16, v84
	v_and_b32_e32 v67, 0xffff0000, v84
	v_lshlrev_b32_e32 v64, 16, v85
	v_lshlrev_b32_e32 v92, 16, v76
	v_and_b32_e32 v93, 0xffff0000, v76
	v_lshlrev_b32_e32 v88, 16, v75
	v_lshlrev_b32_e32 v68, 16, v80
	v_mul_f32_e32 v43, 0xbfb8aa3b, v68
	v_exp_f32_e32 v43, v43
	v_and_b32_e32 v69, 0xffff0000, v80
	v_lshlrev_b32_e32 v90, 16, v81
	v_lshlrev_b32_e32 v72, 16, v79
	v_add_f32_e32 v43, 1.0, v43
	v_rcp_f32_e32 v70, v43
	v_mul_f32_e32 v43, 0xbfb8aa3b, v69
	v_exp_f32_e32 v43, v43
	v_and_b32_e32 v73, 0xffff0000, v79
	v_and_b32_e32 v89, 0xffff0000, v75
	v_lshlrev_b32_e32 v94, 16, v74
	v_add_f32_e32 v43, 1.0, v43
	v_rcp_f32_e32 v71, v43
	v_mul_f32_e32 v43, 0xbfb8aa3b, v90
	v_exp_f32_e32 v43, v43
	v_and_b32_e32 v95, 0xffff0000, v74
	v_lshlrev_b32_e32 v74, 16, v78
	v_and_b32_e32 v75, 0xffff0000, v78
	v_add_f32_e32 v43, 1.0, v43
	v_rcp_f32_e32 v84, v43
	v_mul_f32_e32 v43, 0xbfb8aa3b, v72
	v_exp_f32_e32 v43, v43
	v_mul_f32_e32 v78, 0xbfb8aa3b, v74
	v_mul_f32_e32 v79, 0xbfb8aa3b, v75
	v_exp_f32_e32 v78, v78
	v_add_f32_e32 v43, 1.0, v43
	v_rcp_f32_e32 v76, v43
	v_mul_f32_e32 v43, 0xbfb8aa3b, v73
	v_exp_f32_e32 v43, v43
	v_exp_f32_e32 v79, v79
	v_lshlrev_b32_e32 v86, 16, v77
	v_and_b32_e32 v87, 0xffff0000, v77
	v_add_f32_e32 v43, 1.0, v43
	v_rcp_f32_e32 v77, v43
	v_add_f32_e32 v43, 0, v94
	v_add_f32_e32 v43, v43, v95
	v_add_f32_e32 v43, v43, v88
	v_add_f32_e32 v78, 1.0, v78
	v_add_f32_e32 v79, 1.0, v79
	v_add_f32_e32 v43, v43, v89
	v_rcp_f32_e32 v78, v78
	v_rcp_f32_e32 v79, v79
	v_add_f32_e32 v43, v43, v92
	v_add_f32_e32 v43, v43, v93
	v_add_f32_e32 v43, v43, v86
	v_add_f32_e32 v43, v43, v87
	v_and_b32_e32 v91, 0xffff0000, v81
	v_pk_mul_f32 v[80:81], v[78:79], v[74:75]
	s_nop 0
	v_and_b32_e32 v65, 0xffff0000, v85
	s_waitcnt vmcnt(7)
	v_lshlrev_b32_e32 v100, 16, v107
	v_and_b32_e32 v101, 0xffff0000, v107
	v_lshlrev_b32_e32 v126, 16, v104
	s_nop 0
	s_nop 0
	s_nop 0
	v_and_b32_e32 v127, 0xffff0000, v104
	v_lshlrev_b32_e32 v124, 16, v105
	v_and_b32_e32 v125, 0xffff0000, v105
	v_pk_mul_f32 v[68:69], v[70:71], v[68:69]
	s_nop 0
	s_nop 0
	s_nop 0
	v_lshlrev_b32_e32 v70, 16, v83
	v_and_b32_e32 v71, 0xffff0000, v83
	v_pk_mul_f32 v[72:73], v[76:77], v[72:73]
	v_lshlrev_b32_e32 v76, 16, v82
	s_nop 0
	s_nop 0
	s_nop 0
	v_and_b32_e32 v77, 0xffff0000, v82
	s_waitcnt vmcnt(6)
	v_lshlrev_b32_e32 v82, 16, v112
	v_and_b32_e32 v83, 0xffff0000, v112
	v_lshlrev_b32_e32 v112, 16, v102
	s_nop 0
	s_nop 0
	s_nop 0
	v_lshlrev_b32_e32 v78, 16, v113
	v_and_b32_e32 v79, 0xffff0000, v113
	v_and_b32_e32 v113, 0xffff0000, v102
	v_lshlrev_b32_e32 v98, 16, v111
	s_nop 0
	s_nop 0
	s_nop 0
	v_and_b32_e32 v99, 0xffff0000, v111
	v_lshlrev_b32_e32 v102, 16, v110
	s_nop 0
	s_nop 1
	v_add_f32_dpp v74, v43, v43 quad_perm:[1,0,3,2] row_mask:0xf bank_mask:0xf
	s_nop 1
	v_add_f32_dpp v74, v74, v74 quad_perm:[2,3,0,1] row_mask:0xf bank_mask:0xf
	s_nop 1
	v_add_f32_dpp v74, v74, v74 row_half_mirror row_mask:0xf bank_mask:0xf
	s_nop 1
	v_add_f32_dpp v74, v74, v74 row_mirror row_mask:0xf bank_mask:0xf
	s_nop 1
	v_readlane_b32 s60, v74, 0
	v_readlane_b32 s61, v74, 16
	v_readlane_b32 s62, v74, 32
	v_readlane_b32 s63, v74, 48
	s_nop 2
	v_mov_b32_e32 v43, s60
	v_add_f32_e32 v43, s61, v43
	v_add_f32_e32 v43, s62, v43
	v_add_f32_e32 v43, s63, v43
	v_mul_f32_e32 v74, 0x3b000000, v43
	v_mul_f32_e32 v43, 0xbfb8aa3b, v91
	v_exp_f32_e32 v43, v43
	v_pk_add_f32 v[96:97], v[94:95], v[74:75] op_sel_hi:[1,0] neg_lo:[0,1] neg_hi:[0,1]
	v_pk_add_f32 v[94:95], v[92:93], v[74:75] op_sel_hi:[1,0] neg_lo:[0,1] neg_hi:[0,1]
	v_pk_add_f32 v[88:89], v[88:89], v[74:75] op_sel_hi:[1,0] neg_lo:[0,1] neg_hi:[0,1]
	v_add_f32_e32 v43, 1.0, v43
	v_rcp_f32_e32 v85, v43
	v_pk_add_f32 v[86:87], v[86:87], v[74:75] op_sel_hi:[1,0] neg_lo:[0,1] neg_hi:[0,1]
	v_lshlrev_b32_e32 v74, 16, v109
	v_and_b32_e32 v75, 0xffff0000, v109
	v_pk_mul_f32 v[92:93], v[84:85], v[90:91]
	v_lshlrev_b32_e32 v84, 16, v108
	v_mul_f32_e32 v43, 0xbfb8aa3b, v84
	v_exp_f32_e32 v43, v43
	v_and_b32_e32 v85, 0xffff0000, v108
	v_lshlrev_b32_e32 v108, 16, v103
	v_and_b32_e32 v109, 0xffff0000, v103
	v_add_f32_e32 v43, 1.0, v43
	v_rcp_f32_e32 v90, v43
	v_mul_f32_e32 v43, 0xbfb8aa3b, v85
	v_exp_f32_e32 v43, v43
	v_and_b32_e32 v103, 0xffff0000, v110
	v_mov_b32_e32 v131, v97
	v_pk_mul_f32 v[114:115], v[94:95], v[94:95]
	v_add_f32_e32 v43, 1.0, v43
	v_rcp_f32_e32 v91, v43
	v_mul_f32_e32 v43, 0xbfb8aa3b, v74
	v_exp_f32_e32 v43, v43
	v_pk_mul_f32 v[122:123], v[86:87], v[86:87]
	v_pk_mul_f32 v[90:91], v[90:91], v[84:85]
	v_add_f32_e32 v43, 1.0, v43
	v_rcp_f32_e32 v84, v43
	v_mul_f32_e32 v43, 0xbfb8aa3b, v100
	v_exp_f32_e32 v43, v43
	s_nop 0
	v_add_f32_e32 v43, 1.0, v43
	v_rcp_f32_e32 v104, v43
	v_mul_f32_e32 v43, 0xbfb8aa3b, v101
	v_exp_f32_e32 v43, v43
	s_nop 0
	v_add_f32_e32 v43, 1.0, v43
	v_rcp_f32_e32 v105, v43
	v_add_f32_e32 v43, 0, v112
	v_add_f32_e32 v43, v43, v113
	v_add_f32_e32 v43, v43, v108
	v_pk_mul_f32 v[100:101], v[104:105], v[100:101]
	v_lshlrev_b32_e32 v104, 16, v106
	v_mul_f32_e32 v85, 0xbfb8aa3b, v104
	v_exp_f32_e32 v85, v85
	v_and_b32_e32 v105, 0xffff0000, v106
	v_add_f32_e32 v43, v43, v109
	v_add_f32_e32 v43, v43, v126
	v_add_f32_e32 v85, 1.0, v85
	v_rcp_f32_e32 v106, v85
	v_mul_f32_e32 v85, 0xbfb8aa3b, v105
	v_exp_f32_e32 v85, v85
	v_add_f32_e32 v43, v43, v127
	v_add_f32_e32 v43, v43, v124
	v_add_f32_e32 v43, v43, v125
	v_add_f32_e32 v85, 1.0, v85
	v_rcp_f32_e32 v107, v85
	s_nop 0
	v_pk_mul_f32 v[104:105], v[106:107], v[104:105]
	s_nop 0
	s_nop 0
	s_nop 0
	s_nop 0
	s_nop 0
	s_nop 0
	s_nop 0
	s_nop 0
	s_nop 0
	s_nop 0
	s_nop 0
	s_nop 0
	s_nop 0
	s_nop 0
	s_nop 0
	s_nop 0
	s_nop 1
	v_add_f32_dpp v85, v43, v43 quad_perm:[1,0,3,2] row_mask:0xf bank_mask:0xf
	s_nop 1
	v_add_f32_dpp v85, v85, v85 quad_perm:[2,3,0,1] row_mask:0xf bank_mask:0xf
	s_nop 1
	v_add_f32_dpp v85, v85, v85 row_half_mirror row_mask:0xf bank_mask:0xf
	s_nop 1
	v_add_f32_dpp v85, v85, v85 row_mirror row_mask:0xf bank_mask:0xf
	s_nop 1
	v_readlane_b32 s60, v85, 0
	v_readlane_b32 s61, v85, 16
	v_readlane_b32 s62, v85, 32
	v_readlane_b32 s63, v85, 48
	s_nop 2
	v_mov_b32_e32 v43, s60
	v_add_f32_e32 v43, s61, v43
	v_add_f32_e32 v43, s62, v43
	v_add_f32_e32 v43, s63, v43
	v_mul_f32_e32 v128, 0x3b000000, v43
	v_pk_add_f32 v[110:111], v[112:113], v[128:129] op_sel_hi:[1,0] neg_lo:[0,1] neg_hi:[0,1]
	v_pk_add_f32 v[106:107], v[108:109], v[128:129] op_sel_hi:[1,0] neg_lo:[0,1] neg_hi:[0,1]
	v_mov_b32_e32 v130, v111
	v_mov_b32_e32 v112, v110
	v_mov_b32_e32 v113, v96
	v_pk_mul_f32 v[130:131], v[130:131], v[130:131]
	v_pk_add_f32 v[108:109], v[126:127], v[128:129] op_sel_hi:[1,0] neg_lo:[0,1] neg_hi:[0,1]
	v_pk_fma_f32 v[112:113], v[112:113], v[112:113], v[130:131]
	v_mov_b32_e32 v130, v106
	v_mov_b32_e32 v131, v88
	v_pk_mul_f32 v[126:127], v[108:109], v[108:109]
	v_pk_fma_f32 v[112:113], v[130:131], v[130:131], v[112:113]
	v_mov_b32_e32 v130, v107
	v_mov_b32_e32 v131, v89
	v_pk_fma_f32 v[112:113], v[130:131], v[130:131], v[112:113]
	v_mov_b32_e32 v130, v126
	v_mov_b32_e32 v131, v114
	v_pk_add_f32 v[130:131], v[130:131], v[112:113]
	v_pk_add_f32 v[112:113], v[124:125], v[128:129] op_sel_hi:[1,0] neg_lo:[0,1] neg_hi:[0,1]
	v_mov_b32_e32 v114, v127
	v_pk_mul_f32 v[124:125], v[112:113], v[112:113]
	v_pk_add_f32 v[114:115], v[114:115], v[130:131]
	v_mov_b32_e32 v126, v124
	v_mov_b32_e32 v127, v122
	v_pk_add_f32 v[114:115], v[126:127], v[114:115]
	v_mov_b32_e32 v122, v125
	v_pk_add_f32 v[114:115], v[122:123], v[114:115]
	s_nop 0
	s_nop 0
	s_nop 0
	s_nop 0
	s_nop 0
	s_nop 0
	s_nop 0
	s_nop 0
	s_nop 0
	s_nop 0
	s_nop 0
	s_nop 0
	s_nop 0
	s_nop 0
	s_nop 0
	s_nop 0
	s_nop 0
	s_nop 0
	s_nop 0
	s_nop 0
	s_nop 0
	s_nop 0
	s_nop 0
	s_nop 1
	v_add_f32_dpp v122, v114, v114 quad_perm:[1,0,3,2] row_mask:0xf bank_mask:0xf
	s_nop 1
	v_add_f32_dpp v122, v122, v122 quad_perm:[2,3,0,1] row_mask:0xf bank_mask:0xf
	s_nop 1
	v_add_f32_dpp v122, v122, v122 row_half_mirror row_mask:0xf bank_mask:0xf
	s_nop 1
	v_add_f32_dpp v122, v122, v122 row_mirror row_mask:0xf bank_mask:0xf
	v_add_f32_dpp v123, v115, v115 quad_perm:[1,0,3,2] row_mask:0xf bank_mask:0xf
	s_nop 1
	v_add_f32_dpp v123, v123, v123 quad_perm:[2,3,0,1] row_mask:0xf bank_mask:0xf
	s_nop 1
	v_add_f32_dpp v123, v123, v123 row_half_mirror row_mask:0xf bank_mask:0xf
	s_nop 1
	v_add_f32_dpp v123, v123, v123 row_mirror row_mask:0xf bank_mask:0xf
	s_nop 1
	v_readlane_b32 s60, v122, 0
	v_readlane_b32 s61, v122, 16
	v_readlane_b32 s62, v122, 32
	v_readlane_b32 s63, v122, 48
	s_nop 2
	v_mov_b32_e32 v122, s60
	v_add_f32_e32 v122, s61, v122
	v_add_f32_e32 v122, s62, v122
	v_add_f32_e32 v122, s63, v122
	v_readlane_b32 s60, v123, 0
	v_readlane_b32 s61, v123, 16
	v_readlane_b32 s62, v123, 32
	v_readlane_b32 s63, v123, 48
	s_nop 2
	v_mov_b32_e32 v123, s60
	v_add_f32_e32 v123, s61, v123
	v_add_f32_e32 v123, s62, v123
	v_add_f32_e32 v123, s63, v123
	v_mov_b64_e32 v[114:115], s[4:5]
	v_pk_fma_f32 v[122:123], v[122:123], s[16:17], v[114:115] op_sel_hi:[1,0,0]
	s_nop 0
	v_mul_f32_e32 v43, 0x4b800000, v123
	v_cmp_gt_f32_e64 s[4:5], s71, v123
	v_cmp_gt_f32_e32 vcc, s71, v122
	s_nop 0
	v_cndmask_b32_e64 v43, v123, v43, s[4:5]
	v_rsq_f32_e32 v43, v43
	s_nop 0
	v_mul_f32_e32 v85, 0x45800000, v43
	v_cndmask_b32_e64 v124, v43, v85, s[4:5]
	v_pk_mul_f32 v[96:97], v[96:97], v[124:125] op_sel_hi:[1,0]
	v_mul_f32_e32 v43, 0x4b800000, v122
	s_waitcnt vmcnt(0)
	v_pk_mul_f32 v[34:35], v[34:35], v[96:97]
	v_cndmask_b32_e32 v43, v122, v43, vcc
	s_waitcnt vmcnt(0)
	v_pk_fma_f32 v[34:35], v[38:39], v[76:77], v[34:35]
	v_pk_mul_f32 v[38:39], v[94:95], v[124:125] op_sel_hi:[1,0]
	v_pk_mul_f32 v[34:35], v[80:81], v[34:35]
	v_pk_mul_f32 v[26:27], v[26:27], v[38:39]
	v_rsq_f32_e32 v43, v43
	v_pk_fma_f32 v[26:27], v[30:31], v[66:67], v[26:27]
	v_lshlrev_b32_e32 v76, 16, v15
	v_pk_mul_f32 v[30:31], v[68:69], v[26:27]
	v_pk_mul_f32 v[26:27], v[88:89], v[124:125] op_sel_hi:[1,0]
	v_and_b32_e32 v77, 0xffff0000, v15
	v_pk_mul_f32 v[26:27], v[36:37], v[26:27]
	v_lshlrev_b32_e32 v68, 16, v17
	v_pk_fma_f32 v[26:27], v[40:41], v[70:71], v[26:27]
	v_lshlrev_b32_e32 v70, 16, v24
	v_pk_mul_f32 v[36:37], v[72:73], v[26:27]
	v_pk_mul_f32 v[26:27], v[86:87], v[124:125] op_sel_hi:[1,0]
	v_and_b32_e32 v71, 0xffff0000, v24
	v_pk_mul_f32 v[26:27], v[28:29], v[26:27]
	v_cvt_pk_bf16_f32 v28, v30, v31
	v_pk_fma_f32 v[26:27], v[32:33], v[64:65], v[26:27]
	v_mul_f32_e32 v64, 0x45800000, v43
	v_pk_mul_f32 v[32:33], v[92:93], v[26:27]
	v_cvt_pk_bf16_f32 v26, v34, v35
	v_cvt_pk_bf16_f32 v27, v36, v37
	v_cvt_pk_bf16_f32 v29, v32, v33
	global_store_dwordx4 v[62:63], v[26:29], off
	s_nop 1
	v_mov_b32_e32 v26, v148
	v_mov_b32_e32 v27, v149
	v_mov_b32_e32 v28, v150
	v_mov_b32_e32 v29, v151
	s_nop 0
	v_mov_b32_e32 v30, v152
	v_mov_b32_e32 v31, v153
	v_mov_b32_e32 v32, v154
	v_mov_b32_e32 v33, v155
	v_mov_b32_e32 v34, v156
	v_mov_b32_e32 v35, v157
	v_mov_b32_e32 v36, v158
	v_mov_b32_e32 v37, v159
	v_mov_b32_e32 v38, v160
	v_mov_b32_e32 v39, v161
	v_mov_b32_e32 v40, v162
	v_mov_b32_e32 v41, v163
	v_cndmask_b32_e32 v64, v43, v64, vcc
	v_pk_mul_f32 v[66:67], v[110:111], v[64:65] op_sel_hi:[1,0]
	v_lshlrev_b32_e32 v24, 16, v20
	v_and_b32_e32 v69, 0xffff0000, v17
	v_lshlrev_b32_e32 v72, 16, v23
	v_and_b32_e32 v73, 0xffff0000, v23
	v_and_b32_e32 v23, 0xffff0000, v18
	v_lshlrev_b32_e32 v86, 16, v12
	v_and_b32_e32 v87, 0xffff0000, v12
	v_lshlrev_b32_e32 v12, 16, v8
	v_lshlrev_b32_e32 v88, 16, v4
	v_and_b32_e32 v89, 0xffff0000, v4
	v_mul_f32_e32 v4, 0xbfb8aa3b, v12
	v_exp_f32_e32 v4, v4
	v_lshlrev_b32_e32 v94, 16, v3
	v_and_b32_e32 v95, 0xffff0000, v3
	v_add_f32_e32 v4, 1.0, v4
	v_rcp_f32_e32 v4, v4
	s_nop 0
	v_pk_mul_f32 v[30:31], v[30:31], v[66:67]
	v_lshlrev_b32_e32 v66, 16, v21
	s_nop 0
	v_pk_fma_f32 v[30:31], v[38:39], v[102:103], v[30:31]
	v_pk_mul_f32 v[38:39], v[108:109], v[64:65] op_sel_hi:[1,0]
	v_and_b32_e32 v67, 0xffff0000, v21
	v_pk_mul_f32 v[26:27], v[26:27], v[38:39]
	v_and_b32_e32 v21, 0xffff0000, v16
	v_pk_fma_f32 v[26:27], v[34:35], v[82:83], v[26:27]
	v_lshlrev_b32_e32 v82, 16, v9
	v_pk_mul_f32 v[34:35], v[90:91], v[26:27]
	v_pk_mul_f32 v[26:27], v[106:107], v[64:65] op_sel_hi:[1,0]
	v_and_b32_e32 v83, 0xffff0000, v9
	v_pk_mul_f32 v[26:27], v[32:33], v[26:27]
	v_and_b32_e32 v9, 0xffff0000, v7
	v_pk_fma_f32 v[26:27], v[40:41], v[98:99], v[26:27]
	v_lshlrev_b32_e32 v98, 16, v2
	v_pk_mul_f32 v[32:33], v[100:101], v[26:27]
	v_pk_mul_f32 v[26:27], v[112:113], v[64:65] op_sel_hi:[1,0]
	v_lshlrev_b32_e32 v64, 16, v25
	v_pk_mul_f32 v[26:27], v[28:29], v[26:27]
	v_mul_f32_e32 v28, 0xbfb8aa3b, v75
	v_exp_f32_e32 v28, v28
	v_pk_fma_f32 v[26:27], v[36:37], v[78:79], v[26:27]
	v_and_b32_e32 v65, 0xffff0000, v25
	v_and_b32_e32 v25, 0xffff0000, v20
	v_add_f32_e32 v28, 1.0, v28
	v_rcp_f32_e32 v85, v28
	v_lshlrev_b32_e32 v20, 16, v16
	v_mul_f32_e32 v16, 0xbfb8aa3b, v24
	v_mul_f32_e32 v17, 0xbfb8aa3b, v25
	v_pk_mul_f32 v[28:29], v[84:85], v[74:75]
	v_lshlrev_b32_e32 v74, 16, v19
	v_mul_f32_e32 v15, 0xbfb8aa3b, v74
	v_exp_f32_e32 v15, v15
	v_and_b32_e32 v75, 0xffff0000, v19
	v_exp_f32_e32 v16, v16
	v_exp_f32_e32 v17, v17
	v_add_f32_e32 v15, 1.0, v15
	v_rcp_f32_e32 v78, v15
	v_mul_f32_e32 v15, 0xbfb8aa3b, v75
	v_exp_f32_e32 v15, v15
	v_add_f32_e32 v16, 1.0, v16
	v_add_f32_e32 v17, 1.0, v17
	v_rcp_f32_e32 v16, v16
	v_add_f32_e32 v15, 1.0, v15
	v_rcp_f32_e32 v79, v15
	v_rcp_f32_e32 v17, v17
	v_and_b32_e32 v19, 0xffff0000, v14
	v_mul_f32_e32 v15, 0xbfb8aa3b, v23
	v_pk_mul_f32 v[74:75], v[78:79], v[74:75]
	v_lshlrev_b32_e32 v78, 16, v22
	v_and_b32_e32 v79, 0xffff0000, v22
	v_lshlrev_b32_e32 v22, 16, v18
	v_lshlrev_b32_e32 v18, 16, v14
	v_add_f32_e32 v14, 0, v78
	v_pk_mul_f32 v[16:17], v[16:17], v[24:25]
	v_add_f32_e32 v25, v14, v79
	v_mul_f32_e32 v14, 0xbfb8aa3b, v22
	v_exp_f32_e32 v14, v14
	v_exp_f32_e32 v15, v15
	v_mul_f32_e32 v24, 0xbfb8aa3b, v66
	v_exp_f32_e32 v24, v24
	v_add_f32_e32 v14, 1.0, v14
	v_add_f32_e32 v15, 1.0, v15
	v_rcp_f32_e32 v14, v14
	v_rcp_f32_e32 v15, v15
	v_add_f32_e32 v24, 1.0, v24
	v_rcp_f32_e32 v24, v24
	v_lshlrev_b32_e32 v84, 16, v5
	v_pk_mul_f32 v[14:15], v[14:15], v[22:23]
	v_add_f32_e32 v22, v25, v72
	v_mul_f32_e32 v25, 0xbfb8aa3b, v67
	v_exp_f32_e32 v25, v25
	v_and_b32_e32 v85, 0xffff0000, v5
	v_and_b32_e32 v99, 0xffff0000, v2
	v_add_f32_e32 v22, v22, v73
	v_add_f32_e32 v25, 1.0, v25
	v_rcp_f32_e32 v25, v25
	v_add_f32_e32 v22, v22, v70
	v_add_f32_e32 v22, v22, v71
	v_add_f32_e32 v22, v22, v64
	v_pk_mul_f32 v[24:25], v[24:25], v[66:67]
	v_lshlrev_b32_e32 v66, 16, v13
	v_and_b32_e32 v67, 0xffff0000, v13
	v_and_b32_e32 v13, 0xffff0000, v8
	v_mul_f32_e32 v5, 0xbfb8aa3b, v13
	v_exp_f32_e32 v5, v5
	v_lshlrev_b32_e32 v8, 16, v7
	v_mul_f32_e32 v3, 0xbfb8aa3b, v8
	v_exp_f32_e32 v3, v3
	v_add_f32_e32 v5, 1.0, v5
	v_rcp_f32_e32 v5, v5
	v_add_f32_e32 v22, v22, v65
	v_add_f32_e32 v3, 1.0, v3
	s_nop 0
	v_pk_mul_f32 v[90:91], v[4:5], v[12:13]
	v_rcp_f32_e32 v12, v3
	v_mul_f32_e32 v3, 0xbfb8aa3b, v9
	v_exp_f32_e32 v3, v3
	v_mul_f32_e32 v4, 0xbfb8aa3b, v82
	v_exp_f32_e32 v4, v4
	v_and_b32_e32 v5, 0xffff0000, v11
	v_add_f32_e32 v3, 1.0, v3
	v_rcp_f32_e32 v13, v3
	v_add_f32_e32 v4, 1.0, v4
	v_rcp_f32_e32 v92, v4
	v_lshlrev_b32_e32 v4, 16, v11
	v_pk_mul_f32 v[96:97], v[12:13], v[8:9]
	v_lshlrev_b32_e32 v8, 16, v10
	v_and_b32_e32 v9, 0xffff0000, v10
	v_lshlrev_b32_e32 v10, 16, v6
	v_and_b32_e32 v11, 0xffff0000, v6
	v_add_f32_e32 v2, 0, v8
	v_add_f32_e32 v6, v2, v9
	v_mul_f32_e32 v2, 0xbfb8aa3b, v10
	v_mul_f32_e32 v3, 0xbfb8aa3b, v11
	v_exp_f32_e32 v2, v2
	v_exp_f32_e32 v3, v3
	s_nop 0
	s_nop 0
	s_nop 0
	v_add_f32_e32 v2, 1.0, v2
	v_add_f32_e32 v3, 1.0, v3
	v_rcp_f32_e32 v2, v2
	v_rcp_f32_e32 v3, v3
	v_pk_mul_f32 v[30:31], v[104:105], v[30:31]
	v_pk_mul_f32 v[36:37], v[28:29], v[26:27]
	s_nop 0
	s_nop 0
	v_pk_mul_f32 v[100:101], v[2:3], v[10:11]
	v_add_f32_e32 v2, v6, v4
	v_add_f32_e32 v2, v2, v5
	v_add_f32_e32 v2, v2, v86
	v_add_f32_e32 v2, v2, v87
	v_add_f32_e32 v2, v2, v66
	v_add_f32_e32 v2, v2, v67
	s_nop 0
	v_cvt_pk_bf16_f32 v26, v30, v31
	v_cvt_pk_bf16_f32 v27, v32, v33
	v_cvt_pk_bf16_f32 v28, v34, v35
	v_cvt_pk_bf16_f32 v29, v36, v37
	s_nop 0
	s_nop 0
	s_nop 0
	s_nop 0
	global_store_dwordx4 v[62:63], v[26:29], off offset:1024
	s_nop 1
	v_mov_b32_e32 v26, v164
	v_mov_b32_e32 v27, v165
	v_mov_b32_e32 v28, v166
	v_mov_b32_e32 v29, v167
	s_nop 0
	v_mov_b32_e32 v30, v168
	v_mov_b32_e32 v31, v169
	v_mov_b32_e32 v32, v170
	v_mov_b32_e32 v33, v171
	v_mov_b32_e32 v34, v172
	v_mov_b32_e32 v35, v173
	v_mov_b32_e32 v36, v174
	v_mov_b32_e32 v37, v175
	v_mov_b32_e32 v38, v186
	v_mov_b32_e32 v39, v187
	v_mov_b32_e32 v40, v188
	v_mov_b32_e32 v41, v189
	s_nop 0
	s_nop 0
	s_nop 0
	s_nop 0
	s_nop 0
	s_nop 0
	s_nop 0
	s_nop 0
	s_nop 0
	s_nop 0
	s_nop 0
	s_nop 0
	s_nop 0
	s_nop 0
	s_nop 0
	s_nop 0
	s_nop 0
	s_nop 0
	s_nop 0
	s_nop 0
	s_nop 0
	s_nop 0
	s_nop 1
	v_add_f32_dpp v23, v22, v22 quad_perm:[1,0,3,2] row_mask:0xf bank_mask:0xf
	s_nop 1
	v_add_f32_dpp v23, v23, v23 quad_perm:[2,3,0,1] row_mask:0xf bank_mask:0xf
	s_nop 1
	v_add_f32_dpp v23, v23, v23 row_half_mirror row_mask:0xf bank_mask:0xf
	s_nop 1
	v_add_f32_dpp v23, v23, v23 row_mirror row_mask:0xf bank_mask:0xf
	s_nop 1
	v_readlane_b32 s60, v23, 0
	v_readlane_b32 s61, v23, 16
	v_readlane_b32 s62, v23, 32
	v_readlane_b32 s63, v23, 48
	s_nop 2
	v_mov_b32_e32 v22, s60
	v_add_f32_e32 v22, s61, v22
	v_add_f32_e32 v22, s62, v22
	v_add_f32_e32 v22, s63, v22
	v_mul_f32_e32 v22, 0x3b000000, v22
	v_pk_add_f32 v[78:79], v[78:79], v[22:23] op_sel_hi:[1,0] neg_lo:[0,1] neg_hi:[0,1]
	v_pk_add_f32 v[72:73], v[72:73], v[22:23] op_sel_hi:[1,0] neg_lo:[0,1] neg_hi:[0,1]
	s_nop 0
	s_nop 1
	v_add_f32_dpp v3, v2, v2 quad_perm:[1,0,3,2] row_mask:0xf bank_mask:0xf
	s_nop 1
	v_add_f32_dpp v3, v3, v3 quad_perm:[2,3,0,1] row_mask:0xf bank_mask:0xf
	s_nop 1
	v_add_f32_dpp v3, v3, v3 row_half_mirror row_mask:0xf bank_mask:0xf
	s_nop 1
	v_add_f32_dpp v3, v3, v3 row_mirror row_mask:0xf bank_mask:0xf
	s_nop 1
	v_readlane_b32 s60, v3, 0
	v_readlane_b32 s61, v3, 16
	v_readlane_b32 s62, v3, 32
	v_readlane_b32 s63, v3, 48
	s_nop 2
	v_mov_b32_e32 v2, s60
	v_add_f32_e32 v2, s61, v2
	v_add_f32_e32 v2, s62, v2
	v_add_f32_e32 v2, s63, v2
	v_mul_f32_e32 v2, 0x3b000000, v2
	v_pk_add_f32 v[102:103], v[8:9], v[2:3] op_sel_hi:[1,0] neg_lo:[0,1] neg_hi:[0,1]
	v_mov_b32_e32 v9, v79
	v_mov_b32_e32 v8, v103
	v_pk_add_f32 v[104:105], v[4:5], v[2:3] op_sel_hi:[1,0] neg_lo:[0,1] neg_hi:[0,1]
	v_mov_b32_e32 v6, v102
	v_mov_b32_e32 v7, v78
	v_pk_mul_f32 v[8:9], v[8:9], v[8:9]
	v_pk_add_f32 v[70:71], v[70:71], v[22:23] op_sel_hi:[1,0] neg_lo:[0,1] neg_hi:[0,1]
	v_pk_add_f32 v[86:87], v[86:87], v[2:3] op_sel_hi:[1,0] neg_lo:[0,1] neg_hi:[0,1]
	v_pk_fma_f32 v[6:7], v[6:7], v[6:7], v[8:9]
	v_mov_b32_e32 v8, v104
	v_mov_b32_e32 v9, v72
	v_pk_mul_f32 v[80:81], v[70:71], v[70:71]
	v_pk_mul_f32 v[4:5], v[86:87], v[86:87]
	v_pk_fma_f32 v[6:7], v[8:9], v[8:9], v[6:7]
	v_mov_b32_e32 v8, v105
	v_mov_b32_e32 v9, v73
	v_pk_add_f32 v[22:23], v[64:65], v[22:23] op_sel_hi:[1,0] neg_lo:[0,1] neg_hi:[0,1]
	v_pk_fma_f32 v[6:7], v[8:9], v[8:9], v[6:7]
	v_mov_b32_e32 v8, v4
	v_mov_b32_e32 v9, v80
	v_pk_add_f32 v[66:67], v[66:67], v[2:3] op_sel_hi:[1,0] neg_lo:[0,1] neg_hi:[0,1]
	v_pk_mul_f32 v[64:65], v[22:23], v[22:23]
	v_pk_add_f32 v[6:7], v[8:9], v[6:7]
	v_pk_mul_f32 v[2:3], v[66:67], v[66:67]
	v_mov_b32_e32 v80, v5
	v_pk_add_f32 v[4:5], v[80:81], v[6:7]
	v_mov_b32_e32 v6, v2
	v_mov_b32_e32 v7, v64
	v_pk_add_f32 v[4:5], v[6:7], v[4:5]
	v_mov_b32_e32 v64, v3
	v_pk_add_f32 v[2:3], v[64:65], v[4:5]
	s_nop 0
	s_nop 0
	s_nop 0
	s_nop 0
	s_nop 0
	s_nop 0
	s_nop 0
	s_nop 0
	s_nop 0
	s_nop 0
	s_nop 0
	s_nop 0
	s_nop 0
	s_nop 0
	s_nop 0
	s_nop 0
	s_nop 0
	s_nop 0
	s_nop 0
	s_nop 0
	s_nop 0
	s_nop 0
	s_nop 0
	s_nop 1
	v_add_f32_dpp v4, v2, v2 quad_perm:[1,0,3,2] row_mask:0xf bank_mask:0xf
	s_nop 1
	v_add_f32_dpp v4, v4, v4 quad_perm:[2,3,0,1] row_mask:0xf bank_mask:0xf
	s_nop 1
	v_add_f32_dpp v4, v4, v4 row_half_mirror row_mask:0xf bank_mask:0xf
	s_nop 1
	v_add_f32_dpp v4, v4, v4 row_mirror row_mask:0xf bank_mask:0xf
	v_add_f32_dpp v5, v3, v3 quad_perm:[1,0,3,2] row_mask:0xf bank_mask:0xf
	s_nop 1
	v_add_f32_dpp v5, v5, v5 quad_perm:[2,3,0,1] row_mask:0xf bank_mask:0xf
	s_nop 1
	v_add_f32_dpp v5, v5, v5 row_half_mirror row_mask:0xf bank_mask:0xf
	s_nop 1
	v_add_f32_dpp v5, v5, v5 row_mirror row_mask:0xf bank_mask:0xf
	s_nop 1
	v_readlane_b32 s60, v4, 0
	v_readlane_b32 s61, v4, 16
	v_readlane_b32 s62, v4, 32
	v_readlane_b32 s63, v4, 48
	s_nop 2
	v_mov_b32_e32 v2, s60
	v_add_f32_e32 v2, s61, v2
	v_add_f32_e32 v2, s62, v2
	v_add_f32_e32 v2, s63, v2
	v_readlane_b32 s60, v5, 0
	v_readlane_b32 s61, v5, 16
	v_readlane_b32 s62, v5, 32
	v_readlane_b32 s63, v5, 48
	s_nop 2
	v_mov_b32_e32 v3, s60
	v_add_f32_e32 v3, s61, v3
	v_add_f32_e32 v3, s62, v3
	v_add_f32_e32 v3, s63, v3
	s_nop 0
	v_pk_fma_f32 v[64:65], v[2:3], s[16:17], v[114:115] op_sel_hi:[1,0,0]
	s_nop 0
	v_mul_f32_e32 v2, 0x4b800000, v65
	v_cmp_gt_f32_e64 s[4:5], s71, v65
	v_cmp_gt_f32_e32 vcc, s71, v64
	s_nop 0
	v_cndmask_b32_e64 v2, v65, v2, s[4:5]
	v_rsq_f32_e32 v2, v2
	s_nop 0
	v_mul_f32_e32 v3, 0x45800000, v2
	v_cndmask_b32_e64 v2, v2, v3, s[4:5]
	v_pk_mul_f32 v[4:5], v[78:79], v[2:3] op_sel_hi:[1,0]
	v_pk_mul_f32 v[6:7], v[70:71], v[2:3] op_sel_hi:[1,0]
	v_pk_mul_f32 v[8:9], v[72:73], v[2:3] op_sel_hi:[1,0]
	v_pk_mul_f32 v[2:3], v[22:23], v[2:3] op_sel_hi:[1,0]
	s_nop 0
	v_pk_mul_f32 v[4:5], v[30:31], v[4:5]
	v_pk_mul_f32 v[6:7], v[26:27], v[6:7]
	v_pk_mul_f32 v[8:9], v[32:33], v[8:9]
	v_pk_mul_f32 v[2:3], v[28:29], v[2:3]
	s_nop 0
	v_pk_fma_f32 v[4:5], v[38:39], v[18:19], v[4:5]
	v_pk_fma_f32 v[6:7], v[34:35], v[20:21], v[6:7]
	v_pk_fma_f32 v[8:9], v[40:41], v[76:77], v[8:9]
	v_pk_fma_f32 v[2:3], v[36:37], v[68:69], v[2:3]
	v_pk_mul_f32 v[4:5], v[14:15], v[4:5]
	v_pk_mul_f32 v[6:7], v[16:17], v[6:7]
	v_pk_mul_f32 v[8:9], v[74:75], v[8:9]
	v_pk_mul_f32 v[10:11], v[24:25], v[2:3]
	v_cvt_pk_bf16_f32 v2, v4, v5
	v_cvt_pk_bf16_f32 v3, v8, v9
	v_cvt_pk_bf16_f32 v4, v6, v7
	v_cvt_pk_bf16_f32 v5, v10, v11
	global_store_dwordx4 v[62:63], v[2:5], off offset:2048
	s_nop 1
	v_mov_b32_e32 v2, v190
	v_mov_b32_e32 v3, v191
	v_mov_b32_e32 v4, v192
	v_mov_b32_e32 v5, v193
	s_nop 0
	v_mov_b32_e32 v6, v194
	v_mov_b32_e32 v7, v195
	v_mov_b32_e32 v8, v196
	v_mov_b32_e32 v9, v197
	v_mov_b32_e32 v10, v198
	v_mov_b32_e32 v11, v199
	v_mov_b32_e32 v12, v200
	v_mov_b32_e32 v13, v201
	v_mov_b32_e32 v14, v202
	v_mov_b32_e32 v15, v203
	v_mov_b32_e32 v16, v204
	v_mov_b32_e32 v17, v205
	v_mul_f32_e32 v18, 0x4b800000, v64
	v_cndmask_b32_e32 v18, v64, v18, vcc
	v_rsq_f32_e32 v18, v18
	s_nop 0
	v_mul_f32_e32 v19, 0x45800000, v18
	v_cndmask_b32_e32 v18, v18, v19, vcc
	v_pk_mul_f32 v[20:21], v[102:103], v[18:19] op_sel_hi:[1,0]
	v_cmp_lt_i32_e32 vcc, s14, v42
	s_or_b64 s[12:13], vcc, s[12:13]
	s_nop 0
	v_pk_mul_f32 v[6:7], v[6:7], v[20:21]
	s_nop 0
	v_pk_fma_f32 v[6:7], v[14:15], v[98:99], v[6:7]
	v_pk_mul_f32 v[14:15], v[86:87], v[18:19] op_sel_hi:[1,0]
	v_pk_mul_f32 v[6:7], v[100:101], v[6:7]
	v_pk_mul_f32 v[2:3], v[2:3], v[14:15]
	s_nop 0
	v_pk_fma_f32 v[2:3], v[10:11], v[88:89], v[2:3]
	s_nop 0
	v_pk_mul_f32 v[10:11], v[90:91], v[2:3]
	v_pk_mul_f32 v[2:3], v[104:105], v[18:19] op_sel_hi:[1,0]
	s_nop 0
	v_pk_mul_f32 v[2:3], v[8:9], v[2:3]
	s_nop 0
	v_pk_fma_f32 v[2:3], v[16:17], v[94:95], v[2:3]
	s_nop 0
	v_pk_mul_f32 v[8:9], v[96:97], v[2:3]
	v_pk_mul_f32 v[2:3], v[66:67], v[18:19] op_sel_hi:[1,0]
	s_nop 0
	v_pk_mul_f32 v[2:3], v[4:5], v[2:3]
	v_mul_f32_e32 v4, 0xbfb8aa3b, v83
	v_exp_f32_e32 v4, v4
	v_pk_fma_f32 v[2:3], v[12:13], v[84:85], v[2:3]
	v_add_f32_e32 v4, 1.0, v4
	v_rcp_f32_e32 v93, v4
	s_nop 0
	v_pk_mul_f32 v[4:5], v[92:93], v[82:83]
	s_nop 0
	v_pk_mul_f32 v[12:13], v[4:5], v[2:3]
	v_cvt_pk_bf16_f32 v2, v6, v7
	v_cvt_pk_bf16_f32 v3, v8, v9
	v_cvt_pk_bf16_f32 v4, v10, v11
	v_cvt_pk_bf16_f32 v5, v12, v13
	global_store_dwordx4 v[62:63], v[2:5], off offset:3072
	s_andn2_b64 exec, exec, s[12:13]
	s_cbranch_execnz .LBB0_871
